# prep2: the 16 loop-invariant alpha_up row loads hoisted out of the per-row loop (were load+vmcnt(0) serialized)
# speedup vs baseline: 1.0153x; 1.0141x over previous
; __device__ __forceinline__ void prep2_phase(const Args& a, int e) {
;     ...
;     const int c8 = 8 * lane, h = lane >> 3;
;     float mur[8], muk[8], muv[8], w0[8], a0[8], kkw[8], kaw[8];
;     load8f(mu + c8, mur); load8f(mu + 512 + c8, muk); load8f(mu + 1024 + c8, muv);
;     load8f(a.in[9] + (size_t)e * 512 + c8, w0); load8f(a.in[11] + (size_t)e * 512 + c8, a0);
;     load8f(a.in[14] + (size_t)e * 512 + c8, kkw); load8f(a.in[15] + (size_t)e * 512 + c8, kaw);
;     const float* aup = a.in[19] + (size_t)e * 16 * 256; const f32x4 ab = *(const f32x4*)(a.in[20] + (size_t)e * 256 + 4 * lane);
;     for (int m = gw; m < MT; m += ngw) {
;         const bf16* pr = PA + (size_t)m * APROJ;
;     ...
;         for (int i = 0; i < 16; ++i) { const f32x4 wv = *(const f32x4*)(aup + i * 256 + 4 * lane); acc += xa[i] * wv; }
.LBB0_260:
	s_and_b64 vcc, exec, s[0:1]
	s_mov_b32 s52, 0x10000
	s_mov_b32 s53, 0x103ff
	s_mov_b32 s59, 0xffff
	s_cbranch_vccz .LBB0_273
	v_writelane_b32 v254, s36, 58
	s_mul_i32 s0, s31, 0x1c00
	s_mul_hi_u32 s1, s30, 0x1c00
	v_writelane_b32 v254, s37, 59
	s_add_i32 s1, s1, s0
	s_mul_i32 s0, s30, 0x1c00
	v_readlane_b32 s68, v254, 2
	s_add_u32 s46, s84, s0
	v_readlane_b32 s72, v254, 6
	v_readlane_b32 s73, v254, 7
	s_addc_u32 s47, s85, s1
	s_mul_i32 s0, s31, 0x1c000
	s_mul_hi_u32 s1, s30, 0x1c000
	v_readlane_b32 s74, v254, 8
	v_readlane_b32 s75, v254, 9
	v_readlane_b32 s76, v254, 10
	v_readlane_b32 s77, v254, 11
	s_mov_b64 s[40:41], s[72:73]
	s_add_i32 s1, s1, s0
	s_mul_i32 s0, s30, 0x1c000
	s_mov_b64 s[42:43], s[74:75]
	s_add_u32 s48, s42, s0
	s_addc_u32 s49, s43, s1
	v_readlane_b32 s0, v254, 29
	s_cmp_gt_i32 s0, 2
	s_mov_b64 s[0:1], -1
	s_movk_i32 s34, 0x1c00
	s_mov_b32 s42, 0x31000000
	s_mov_b32 s50, 0x800000
	v_readlane_b32 s69, v254, 3
	v_readlane_b32 s70, v254, 4
	v_readlane_b32 s71, v254, 5
	v_readlane_b32 s78, v254, 12
	v_readlane_b32 s79, v254, 13
	v_readlane_b32 s80, v254, 14
	v_readlane_b32 s81, v254, 15
	v_readlane_b32 s82, v254, 16
	v_readlane_b32 s83, v254, 17
	s_mov_b64 s[44:45], s[76:77]
	s_cbranch_scc0 .LBB0_275
	v_mov_b32_e32 v92, v159
	s_mov_b32 s0, 0x10400
	v_ashrrev_i32_e32 v0, 6, v92
	v_add_u32_e32 v62, s33, v0
	v_cmp_gt_i32_e32 vcc, s0, v62
	s_and_saveexec_b64 s[40:41], vcc
	s_cbranch_execz .LBB0_274
	v_readlane_b32 s0, v254, 62
	v_readlane_b32 s1, v254, 63
	s_lshl_b64 s[0:1], s[0:1], 2
	s_add_u32 s10, s86, s0
	v_and_b32_e32 v63, 63, v92
	s_addc_u32 s11, s87, s1
	v_lshlrev_b32_e32 v0, 5, v63
	s_add_u32 s12, s90, s0
	s_mov_b64 s[44:45], 0x1000
	s_movk_i32 s3, 0x1000
	s_waitcnt vmcnt(0)
	v_lshl_add_u64 v[18:19], s[46:47], 0, v[0:1]
	s_addc_u32 s13, s91, s1
	v_lshl_add_u64 v[22:23], v[18:19], 0, s[44:45]
	v_add_co_u32_e32 v18, vcc, s3, v18
	s_add_u32 s14, s98, s0
	s_nop 0
	v_addc_co_u32_e32 v19, vcc, 0, v19, vcc
	s_addc_u32 s15, s99, s1
	v_readlane_b32 s68, v251, 4
	global_load_dwordx4 v[2:5], v0, s[46:47] offset:16
	global_load_dwordx4 v[6:9], v0, s[46:47]
	global_load_dwordx4 v[10:13], v0, s[46:47] offset:2064
	global_load_dwordx4 v[14:17], v0, s[46:47] offset:2048
	s_nop 0
	global_load_dwordx4 v[18:21], v[18:19], off
	s_nop 0
	global_load_dwordx4 v[22:25], v[22:23], off offset:16
	s_nop 0
	global_load_dwordx4 v[26:29], v0, s[10:11]
	global_load_dwordx4 v[30:33], v0, s[10:11] offset:16
	global_load_dwordx4 v[34:37], v0, s[12:13]
	global_load_dwordx4 v[38:41], v0, s[12:13] offset:16
	global_load_dwordx4 v[42:45], v0, s[14:15]
	global_load_dwordx4 v[46:49], v0, s[14:15] offset:16
	s_lshl_b64 s[16:17], s[30:31], 10
	v_readlane_b32 s76, v251, 12
	v_readlane_b32 s77, v251, 13
	s_add_u32 s16, s76, s16
	s_addc_u32 s17, s77, s17
	s_add_u32 s0, s96, s0
	v_lshlrev_b32_e32 v98, 4, v63
	s_addc_u32 s1, s97, s1
	global_load_dwordx4 v[50:53], v98, s[16:17]
	global_load_dwordx4 v[54:57], v0, s[0:1]
	global_load_dwordx4 v[58:61], v0, s[0:1] offset:16
	v_readlane_b32 s74, v251, 10
	s_lshl_b64 s[0:1], s[30:31], 14
	v_readlane_b32 s75, v251, 11
	s_add_u32 s0, s74, s0
	s_addc_u32 s1, s75, s1
	v_mov_b32_e32 v99, v1
	v_lshl_add_u64 v[64:65], s[0:1], 0, v[98:99]
	s_mov_b64 s[0:1], 0x1400
	v_lshl_add_u64 v[68:69], v[64:65], 0, s[0:1]
	s_mov_b64 s[0:1], 0x1800
	v_lshl_add_u64 v[70:71], v[64:65], 0, s[0:1]
	s_mov_b64 s[0:1], 0x1c00
	v_lshl_add_u64 v[72:73], v[64:65], 0, s[0:1]
	s_mov_b64 s[0:1], 0x2000
	v_lshl_add_u64 v[74:75], v[64:65], 0, s[0:1]
	s_mov_b64 s[0:1], 0x2400
	v_lshl_add_u64 v[76:77], v[64:65], 0, s[0:1]
	s_mov_b64 s[0:1], 0x2800
	v_lshl_add_u64 v[78:79], v[64:65], 0, s[0:1]
	s_mov_b64 s[0:1], 0x2c00
	v_lshl_add_u64 v[80:81], v[64:65], 0, s[0:1]
	s_mov_b64 s[0:1], 0x3000
	v_lshl_add_u64 v[82:83], v[64:65], 0, s[0:1]
	s_mov_b64 s[0:1], 0x3400
	v_lshlrev_b32_e32 v0, 3, v63
	v_bfe_u32 v96, v92, 3, 3
	v_lshl_add_u64 v[84:85], v[64:65], 0, s[0:1]
	s_mov_b64 s[0:1], 0x3800
	v_ashrrev_i32_e32 v63, 31, v62
	v_lshlrev_b32_e32 v92, 4, v92
	v_lshl_add_u64 v[86:87], v[64:65], 0, s[0:1]
	s_mov_b64 s[0:1], 0x3c00
	v_lshlrev_b64 v[90:91], 11, v[62:63]
	v_lshlrev_b32_e32 v93, 8, v96
	v_and_b32_e32 v97, 0x70, v92
	s_movk_i32 s10, 0xe00
	v_readlane_b32 s69, v251, 5
	v_lshl_add_u64 v[88:89], v[64:65], 0, s[0:1]
	v_or3_b32 v90, v90, v93, v97
	v_mad_i64_i32 v[92:93], s[0:1], v62, s10, 0
	v_lshlrev_b64 v[94:95], 12, v[62:63]
	v_lshlrev_b32_e32 v96, 9, v96
	s_mov_b64 s[68:69], 0x31000c00
	v_readlane_b32 s36, v253, 30
	v_readlane_b32 s28, v253, 28
	v_readlane_b32 s18, v253, 24
	v_or3_b32 v94, v94, v96, v97
	v_lshlrev_b64 v[96:97], 10, v[62:63]
	v_or_b32_e32 v100, v92, v0
	v_mov_b32_e32 v101, v93
	s_mov_b32 s65, 0x7f800000
	s_mov_b32 s51, 0x3f317217
	s_mov_b32 s43, 0xbfb8aa3b
	v_readlane_b32 s37, v253, 31
	v_readlane_b32 s29, v253, 29
	v_readlane_b32 s19, v253, 25
	v_lshl_add_u64 v[66:67], v[64:65], 0, s[44:45]
	v_lshl_add_u64 v[94:95], s[20:21], 0, v[94:95]
	v_or_b32_e32 v96, v96, v98
	v_mad_i64_i32 v[98:99], s[0:1], v62, s10, v[98:99]
	v_lshl_add_u64 v[100:101], v[100:101], 0, s[68:69]
	s_mov_b64 s[30:31], 0
	v_lshlrev_b32_e32 v0, 2, v0
	v_readlane_b32 s70, v251, 6
	v_readlane_b32 s71, v251, 7
	v_readlane_b32 s72, v251, 8
	v_readlane_b32 s73, v251, 9
	v_readlane_b32 s78, v251, 14
	v_readlane_b32 s79, v251, 15
	v_readlane_b32 s80, v251, 16
	v_readlane_b32 s81, v251, 17
	v_readlane_b32 s82, v251, 18
	v_readlane_b32 s83, v251, 19
	global_load_dwordx4 v[206:209], v[64:65], off
	global_load_dwordx4 v[210:213], v[64:65], off offset:1024
	global_load_dwordx4 v[214:217], v[64:65], off offset:2048
	global_load_dwordx4 v[218:221], v[64:65], off offset:3072
	global_load_dwordx4 v[222:225], v[66:67], off
	global_load_dwordx4 v[226:229], v[68:69], off
	global_load_dwordx4 v[230:233], v[70:71], off
	global_load_dwordx4 v[234:237], v[72:73], off
	global_load_dwordx4 v[238:241], v[74:75], off
	global_load_dwordx4 v[242:245], v[76:77], off
	global_load_dwordx4 v[246:249], v[78:79], off
	global_load_dwordx4 v[166:169], v[80:81], off
	global_load_dwordx4 v[170:173], v[82:83], off
	global_load_dwordx4 v[174:177], v[84:85], off
	global_load_dwordx4 v[178:181], v[86:87], off
	global_load_dwordx4 v[192:195], v[88:89], off
	s_branch .LBB0_266

; __device__ __forceinline__ float sigmoid_f(float x) { return __builtin_amdgcn_rcpf(1.0f + __expf(-x)); }
; __device__ __forceinline__ void prep2_phase(const Args& a, int e) {
;     ...
;         float lw[8], la[8], u[8], av[8], kk[8], km[8], ka[8];
;         unpack8(*(const v4u*)(Lw + (size_t)m * 512 + c8), lw); unpack8(*(const v4u*)(La + (size_t)m * 512 + c8), la);
;         float ss = 0.f;
; #pragma unroll
;         for (int i = 0; i < 8; ++i) {
;             u[i] = 1.0f - __expf(-0.6065306597126334f * sigmoid_f(w0[i] + lw[i]));
;             av[i] = sigmoid_f(a0[i] + la[i]);
;             kk[i] = k[i] * kkw[i]; ss += kk[i] * kk[i];
;             km[i] = k[i] * (1.0f + (av[i] - 1.0f) * kaw[i]);
;         }
.LBB0_265:
	s_or_b64 exec, exec, s[0:1]
	v_lshl_add_u64 v[130:131], s[22:23], 0, v[96:97]
	s_mov_b32 s0, 0xe780000
	v_add_co_u32_e32 v126, vcc, s0, v130
	s_mov_b32 s0, 0x12880000
	s_nop 0
	v_addc_co_u32_e32 v127, vcc, 0, v131, vcc
	global_load_dwordx4 v[126:129], v[126:127], off
	v_add_u32_e32 v62, s64, v62
	v_lshl_add_u64 v[96:97], v[96:97], 0, s[36:37]
	s_waitcnt vmcnt(0)
	v_lshlrev_b32_e32 v63, 16, v126
	v_and_b32_e32 v133, 0xffff0000, v126
	v_add_co_u32_e32 v126, vcc, s0, v130
	v_lshlrev_b32_e32 v141, 16, v127
	v_and_b32_e32 v143, 0xffff0000, v127
	v_addc_co_u32_e32 v127, vcc, 0, v131, vcc
	v_lshlrev_b32_e32 v149, 16, v128
	v_and_b32_e32 v145, 0xffff0000, v128
	v_lshlrev_b32_e32 v138, 16, v129
	v_and_b32_e32 v136, 0xffff0000, v129
	global_load_dwordx4 v[126:129], v[126:127], off
	v_add_f32_e32 v63, v26, v63
	v_mul_f32_e32 v63, 0xbfb8aa3b, v63
	v_exp_f32_e32 v63, v63
	v_add_f32_e32 v145, v31, v145
	v_mul_f32_e32 v145, 0xbfb8aa3b, v145
	v_exp_f32_e32 v145, v145
	v_add_f32_e32 v63, 1.0, v63
	v_rcp_f32_e32 v63, v63
	s_mov_b32 s0, 0x1aa80000
	v_add_f32_e32 v145, 1.0, v145
	v_rcp_f32_e32 v145, v145
	v_mul_f32_e32 v63, 0xbf1b4598, v63
	v_mul_f32_e32 v63, 0x3fb8aa3b, v63
	v_exp_f32_e32 v63, v63
	v_mul_f32_e32 v145, 0xbf1b4598, v145
	v_mul_f32_e32 v145, 0x3fb8aa3b, v145
	v_exp_f32_e32 v145, v145
	v_sub_f32_e32 v132, 1.0, v63
	v_sub_f32_e32 v145, 1.0, v145
	s_waitcnt vmcnt(0)
	v_lshlrev_b32_e32 v131, 16, v127
	v_and_b32_e32 v147, 0xffff0000, v127
	v_add_f32_e32 v127, v27, v133
	v_mul_f32_e32 v127, 0xbfb8aa3b, v127
	v_exp_f32_e32 v127, v127
	v_lshlrev_b32_e32 v130, 16, v126
	v_add_f32_e32 v63, v34, v130
	v_and_b32_e32 v126, 0xffff0000, v126
	v_mul_f32_e32 v63, 0xbfb8aa3b, v63
	v_exp_f32_e32 v63, v63
	v_add_f32_e32 v127, 1.0, v127
	v_add_f32_e32 v126, v35, v126
	v_rcp_f32_e32 v127, v127
	v_mul_f32_e32 v126, 0xbfb8aa3b, v126
	v_exp_f32_e32 v126, v126
	v_add_f32_e32 v63, 1.0, v63
	v_rcp_f32_e32 v134, v63
	v_mul_f32_e32 v127, 0xbf1b4598, v127
	v_mul_f32_e32 v127, 0x3fb8aa3b, v127
	v_add_f32_e32 v126, 1.0, v126
	v_exp_f32_e32 v127, v127
	v_rcp_f32_e32 v135, v126
	v_add_f32_e32 v63, -1.0, v134
	v_fma_f32 v63, v42, v63, 1.0
	v_mul_f32_e32 v63, v124, v63
	v_sub_f32_e32 v133, 1.0, v127
	v_pk_mul_f32 v[126:127], v[54:55], v[124:125]
	v_add_f32_e32 v124, -1.0, v135
	v_fma_f32 v124, v43, v124, 1.0
	v_mul_f32_e32 v140, v125, v124
	v_add_f32_e32 v124, v28, v141
	v_mul_f32_e32 v124, 0xbfb8aa3b, v124
	v_exp_f32_e32 v124, v124
	v_lshlrev_b32_e32 v148, 16, v128
	v_add_f32_e32 v148, v38, v148
	v_and_b32_e32 v146, 0xffff0000, v128
	v_add_f32_e32 v124, 1.0, v124
	v_rcp_f32_e32 v124, v124
	v_mul_f32_e32 v148, 0xbfb8aa3b, v148
	v_exp_f32_e32 v148, v148
	v_add_f32_e32 v146, v39, v146
	v_mul_f32_e32 v124, 0xbf1b4598, v124
	v_mul_f32_e32 v124, 0x3fb8aa3b, v124
	v_exp_f32_e32 v124, v124
	v_mul_f32_e32 v146, 0xbfb8aa3b, v146
	v_exp_f32_e32 v146, v146
	v_add_f32_e32 v148, 1.0, v148
	v_sub_f32_e32 v142, 1.0, v124
	v_add_f32_e32 v124, v36, v131
	v_mul_f32_e32 v124, 0xbfb8aa3b, v124
	v_exp_f32_e32 v124, v124
	v_rcp_f32_e32 v158, v148
	v_add_f32_e32 v146, 1.0, v146
	v_rcp_f32_e32 v146, v146
	v_add_f32_e32 v124, 1.0, v124
	v_rcp_f32_e32 v144, v124
	v_add_f32_e32 v148, -1.0, v158
	v_fma_f32 v148, v46, v148, 1.0
	v_mul_f32_e32 v160, v118, v148
	v_add_f32_e32 v124, -1.0, v144
	v_fma_f32 v124, v44, v124, 1.0
	v_mul_f32_e32 v141, v122, v124
	v_add_f32_e32 v124, v29, v143
	v_mul_f32_e32 v124, 0xbfb8aa3b, v124
	v_exp_f32_e32 v124, v124
	v_lshlrev_b32_e32 v139, 16, v129
	v_and_b32_e32 v137, 0xffff0000, v129
	v_pk_mul_f32 v[128:129], v[126:127], v[126:127]
	v_add_f32_e32 v124, 1.0, v124
	v_rcp_f32_e32 v124, v124
	s_nop 0
	v_mul_f32_e32 v124, 0xbf1b4598, v124
	v_mul_f32_e32 v124, 0x3fb8aa3b, v124
	v_exp_f32_e32 v124, v124
	s_nop 0
	v_sub_f32_e32 v143, 1.0, v124
	v_add_f32_e32 v124, v37, v147
	v_mul_f32_e32 v124, 0xbfb8aa3b, v124
	v_exp_f32_e32 v124, v124
	s_nop 0
	v_add_f32_e32 v124, 1.0, v124
	v_rcp_f32_e32 v147, v124
	v_pk_mul_f32 v[124:125], v[56:57], v[122:123]
	v_add_f32_e32 v122, -1.0, v147
	v_fma_f32 v122, v45, v122, 1.0
	v_mul_f32_e32 v122, v123, v122
	v_add_f32_e32 v123, v30, v149
	v_pk_mul_f32 v[148:149], v[58:59], v[118:119]
	v_add_f32_e32 v118, -1.0, v146
	v_fma_f32 v118, v47, v118, 1.0
	v_mul_f32_e32 v161, v119, v118
	v_add_f32_e32 v118, v32, v138
	v_mul_f32_e32 v118, 0xbfb8aa3b, v118
	v_exp_f32_e32 v118, v118
	v_pk_mul_f32 v[130:131], v[124:125], v[124:125]
	v_pk_mul_f32 v[156:157], v[148:149], v[148:149]
	v_mul_f32_e32 v123, 0xbfb8aa3b, v123
	v_add_f32_e32 v118, 1.0, v118
	v_rcp_f32_e32 v118, v118
	v_exp_f32_e32 v123, v123
	v_mul_f32_e32 v118, 0xbf1b4598, v118
	v_mul_f32_e32 v118, 0x3fb8aa3b, v118
	v_exp_f32_e32 v118, v118
	v_add_f32_e32 v123, 1.0, v123
	v_rcp_f32_e32 v123, v123
	v_sub_f32_e32 v138, 1.0, v118
	v_add_f32_e32 v118, v40, v139
	v_mul_f32_e32 v118, 0xbfb8aa3b, v118
	v_exp_f32_e32 v118, v118
	v_mul_f32_e32 v123, 0xbf1b4598, v123
	v_mul_f32_e32 v123, 0x3fb8aa3b, v123
	v_exp_f32_e32 v123, v123
	v_add_f32_e32 v118, 1.0, v118
	v_rcp_f32_e32 v139, v118
	v_sub_f32_e32 v123, 1.0, v123
	v_add_f32_e32 v118, -1.0, v139
	v_fma_f32 v118, v48, v118, 1.0
	v_mul_f32_e32 v162, v102, v118
	v_add_f32_e32 v118, v33, v136
	v_mul_f32_e32 v118, 0xbfb8aa3b, v118
	v_exp_f32_e32 v118, v118
	s_nop 0
	v_add_f32_e32 v118, 1.0, v118
	v_rcp_f32_e32 v118, v118
	s_nop 0
	v_mul_f32_e32 v118, 0xbf1b4598, v118
	v_mul_f32_e32 v118, 0x3fb8aa3b, v118
	v_exp_f32_e32 v118, v118
	s_nop 0
	v_sub_f32_e32 v163, 1.0, v118
	v_add_f32_e32 v118, v41, v137
	v_mul_f32_e32 v118, 0xbfb8aa3b, v118
	v_exp_f32_e32 v118, v118
	s_nop 0
	v_add_f32_e32 v118, 1.0, v118
	v_rcp_f32_e32 v164, v118
; __device__ __forceinline__ float sum8_dpp(float x) { x += DPPX(x, 0xB1); x += DPPX(x, 0x4E); x += DPPX(x, 0x141); return x; }
; __device__ __forceinline__ void prep2_phase(const Args& a, int e) {
;     ...
;         ss = sum8_dpp(ss);
;         const float rn = rsqrtf(ss + 1e-12f);
; #pragma unroll
;         for (int i = 0; i < 8; ++i) { kk[i] *= rn; ka[i] = kk[i] * av[i]; }
;         bf16* sa = SA + ((size_t)m * 8 + h) * 256 + (lane & 7) * 8; bf16* sb = SB + ((size_t)m * 8 + h) * 128 + (lane & 7) * 8;
;         *(v4u*)(sa) = pack8(r); *(v4u*)(sa + 64) = pack8(u); *(v4u*)(sa + 128) = pack8(km); *(v4u*)(sa + 192) = pack8(v);
;         *(v4u*)(sb) = pack8(kk); *(v4u*)(sb + 64) = pack8(ka);
;         bf16* pb = PB + (size_t)m * APROJ + 1536;
;         float xa[16]; unpack8(*(const v4u*)(pb), xa); unpack8(*(const v4u*)(pb + 8), xa + 8);
	v_pk_mul_f32 v[118:119], v[60:61], v[102:103]
	v_add_f32_e32 v102, v128, v129
	v_add_f32_e32 v102, v130, v102
	v_add_f32_e32 v102, v131, v102
	v_add_f32_e32 v102, v156, v102
	v_pk_mul_f32 v[136:137], v[118:119], v[118:119]
	v_add_f32_e32 v102, v157, v102
	v_add_f32_e32 v102, v136, v102
	v_add_f32_e32 v102, v137, v102
	v_add_f32_e32 v128, -1.0, v164
	v_fma_f32 v128, v49, v128, 1.0
	v_add_f32_dpp v102, v102, v102 quad_perm:[1,0,3,2] row_mask:0xf bank_mask:0xf bound_ctrl:1
	v_mul_f32_e32 v128, v103, v128
	s_nop 0
	v_add_f32_dpp v102, v102, v102 quad_perm:[2,3,0,1] row_mask:0xf bank_mask:0xf bound_ctrl:1
	s_nop 1
	v_add_f32_dpp v102, v102, v102 row_half_mirror row_mask:0xf bank_mask:0xf bound_ctrl:1
	v_add_f32_e32 v102, 0x2b8cbccc, v102
	v_cmp_gt_f32_e32 vcc, s50, v102
	v_mul_f32_e32 v103, 0x4b800000, v102
	s_nop 0
	v_cndmask_b32_e32 v102, v102, v103, vcc
	v_rsq_f32_e32 v102, v102
	s_nop 0
	v_mul_f32_e32 v103, 0x45800000, v102
	v_cndmask_b32_e32 v102, v102, v103, vcc
	v_mul_f32_e32 v126, v126, v102
	v_mul_f32_e32 v127, v127, v102
	v_mul_f32_e32 v124, v124, v102
	v_mul_f32_e32 v125, v125, v102
	v_mul_f32_e32 v137, v149, v102
	v_mul_f32_e32 v129, v134, v126
	v_mul_f32_e32 v130, v135, v127
	v_mul_f32_e32 v131, v144, v124
	v_mul_f32_e32 v134, v147, v125
	v_mul_f32_e32 v135, v148, v102
	v_mul_f32_e32 v144, v146, v137
	v_mul_f32_e32 v146, v118, v102
	v_mul_f32_e32 v147, v119, v102
	v_cvt_pk_bf16_f32 v102, v106, v107
	v_cvt_pk_bf16_f32 v103, v104, v105
	v_cvt_pk_bf16_f32 v104, v110, v111
	v_cvt_pk_bf16_f32 v105, v108, v109
	global_store_dwordx4 v[94:95], v[102:105], off
	v_lshl_add_u64 v[118:119], s[22:23], 0, v[90:91]
	v_add_co_u32_e32 v106, vcc, s0, v118
	v_cvt_pk_bf16_f32 v102, v132, v133
	v_cvt_pk_bf16_f32 v103, v142, v143
	v_cvt_pk_bf16_f32 v104, v123, v145
	v_cvt_pk_bf16_f32 v105, v138, v163
	global_store_dwordx4 v[94:95], v[102:105], off offset:128
	s_nop 0
	v_addc_co_u32_e32 v107, vcc, 0, v119, vcc
	v_cvt_pk_bf16_f32 v102, v63, v140
	v_cvt_pk_bf16_f32 v103, v141, v122
	v_cvt_pk_bf16_f32 v104, v160, v161
	v_cvt_pk_bf16_f32 v105, v162, v128
	global_store_dwordx4 v[94:95], v[102:105], off offset:256
	v_mul_f32_e32 v136, v158, v135
	v_mul_f32_e32 v139, v139, v146
	v_cvt_pk_bf16_f32 v102, v112, v113
	v_cvt_pk_bf16_f32 v103, v114, v115
	v_cvt_pk_bf16_f32 v104, v116, v117
	v_cvt_pk_bf16_f32 v105, v120, v121
	global_store_dwordx4 v[94:95], v[102:105], off offset:384
	v_mul_f32_e32 v148, v164, v147
	v_lshl_add_u64 v[90:91], v[90:91], 0, s[18:19]
	v_cvt_pk_bf16_f32 v102, v126, v127
	v_cvt_pk_bf16_f32 v103, v124, v125
	v_cvt_pk_bf16_f32 v104, v135, v137
	v_cvt_pk_bf16_f32 v105, v146, v147
	global_store_dwordx4 v[106:107], v[102:105], off
	v_lshl_add_u64 v[94:95], v[94:95], 0, s[28:29]
	s_nop 0
	v_cvt_pk_bf16_f32 v102, v129, v130
	v_cvt_pk_bf16_f32 v103, v131, v134
	v_cvt_pk_bf16_f32 v104, v136, v144
	v_cvt_pk_bf16_f32 v105, v139, v148
	global_store_dwordx4 v[106:107], v[102:105], off offset:128
	s_nop 1
	v_lshl_add_u64 v[102:103], s[22:23], 0, v[92:93]
	v_lshl_add_u64 v[106:107], v[102:103], 0, s[68:69]
	v_add_co_u32_e32 v102, vcc, s42, v102
	s_nop 1
	v_addc_co_u32_e32 v103, vcc, 0, v103, vcc
	global_load_dwordx4 v[102:105], v[102:103], off offset:3072
	s_nop 0
	global_load_dwordx4 v[106:109], v[106:107], off offset:16
	s_waitcnt vmcnt(1)
	v_lshlrev_b32_e32 v118, 16, v104
	v_and_b32_e32 v120, 0xffff0000, v104
	v_lshlrev_b32_e32 v122, 16, v105
	v_and_b32_e32 v124, 0xffff0000, v105
	s_waitcnt vmcnt(0)
; __device__ __forceinline__ unsigned cvt_pk_bf16(float lo, float hi) { unsigned r; asm volatile("v_cvt_pk_bf16_f32 %0, %1, %2" : "=v"(r) : "v"(lo), "v"(hi)); return r; }
; __device__ __forceinline__ float softplus_f(float x) { return fmaxf(x, 0.f) + __logf(1.0f + __expf(-fabsf(x))); }
; __device__ __forceinline__ void prep2_phase(const Args& a, int e) {
;     ...
;         float xa[16]; unpack8(*(const v4u*)(pb), xa); unpack8(*(const v4u*)(pb + 8), xa + 8);
;         f32x4 acc = ab;
; #pragma unroll
;         for (int i = 0; i < 16; ++i) { const f32x4 wv = *(const f32x4*)(aup + i * 256 + 4 * lane); acc += xa[i] * wv; }
;         float ug[4];
; #pragma unroll
;         for (int i = 0; i < 4; ++i) ug[i] = 1.0f - __expf(-softplus_f(-acc[i]) * (1.0f / 16.0f));
;         v2u o; o.x = cvt_pk_bf16(ug[0], ug[1]); o.y = cvt_pk_bf16(ug[2], ug[3]);
;         *(v2u*)(pb + 4 * lane) = o;
	v_lshlrev_b32_e32 v126, 16, v106
	v_and_b32_e32 v128, 0xffff0000, v106
	v_lshlrev_b32_e32 v130, 16, v107
	v_and_b32_e32 v132, 0xffff0000, v107
	s_nop 0
	v_lshlrev_b32_e32 v110, 16, v102
	v_and_b32_e32 v112, 0xffff0000, v102
	v_lshlrev_b32_e32 v114, 16, v103
	v_and_b32_e32 v116, 0xffff0000, v103
	v_lshlrev_b32_e32 v134, 16, v108
	v_and_b32_e32 v108, 0xffff0000, v108
	v_lshlrev_b32_e32 v136, 16, v109
	v_and_b32_e32 v102, 0xffff0000, v109
	v_pk_fma_f32 v[138:139], v[206:207], v[110:111], v[50:51] op_sel_hi:[1,0,1]
	v_pk_fma_f32 v[110:111], v[208:209], v[110:111], v[52:53] op_sel_hi:[1,0,1]
	s_nop 0
	v_pk_fma_f32 v[110:111], v[212:213], v[112:113], v[110:111] op_sel_hi:[1,0,1]
	v_pk_fma_f32 v[112:113], v[210:211], v[112:113], v[138:139] op_sel_hi:[1,0,1]
	s_nop 0
	v_pk_fma_f32 v[112:113], v[214:215], v[114:115], v[112:113] op_sel_hi:[1,0,1]
	v_pk_fma_f32 v[110:111], v[216:217], v[114:115], v[110:111] op_sel_hi:[1,0,1]
	s_nop 0
	v_pk_fma_f32 v[110:111], v[220:221], v[116:117], v[110:111] op_sel_hi:[1,0,1]
	v_pk_fma_f32 v[112:113], v[218:219], v[116:117], v[112:113] op_sel_hi:[1,0,1]
	s_nop 0
	v_pk_fma_f32 v[112:113], v[118:119], v[222:223], v[112:113] op_sel_hi:[0,1,1]
	v_pk_fma_f32 v[110:111], v[118:119], v[224:225], v[110:111] op_sel_hi:[0,1,1]
	s_nop 0
	v_pk_fma_f32 v[110:111], v[120:121], v[228:229], v[110:111] op_sel_hi:[0,1,1]
	v_pk_fma_f32 v[112:113], v[120:121], v[226:227], v[112:113] op_sel_hi:[0,1,1]
	s_nop 0
	v_pk_fma_f32 v[112:113], v[122:123], v[230:231], v[112:113] op_sel_hi:[0,1,1]
	v_pk_fma_f32 v[110:111], v[122:123], v[232:233], v[110:111] op_sel_hi:[0,1,1]
	s_nop 0
	v_pk_fma_f32 v[110:111], v[124:125], v[236:237], v[110:111] op_sel_hi:[0,1,1]
	v_pk_fma_f32 v[112:113], v[124:125], v[234:235], v[112:113] op_sel_hi:[0,1,1]
	s_nop 0
	v_pk_fma_f32 v[112:113], v[126:127], v[238:239], v[112:113] op_sel_hi:[0,1,1]
	v_pk_fma_f32 v[110:111], v[126:127], v[240:241], v[110:111] op_sel_hi:[0,1,1]
	s_nop 0
	v_pk_fma_f32 v[110:111], v[128:129], v[244:245], v[110:111] op_sel_hi:[0,1,1]
	v_pk_fma_f32 v[112:113], v[128:129], v[242:243], v[112:113] op_sel_hi:[0,1,1]
	s_nop 0
	v_pk_fma_f32 v[112:113], v[130:131], v[246:247], v[112:113] op_sel_hi:[0,1,1]
	v_pk_fma_f32 v[110:111], v[130:131], v[248:249], v[110:111] op_sel_hi:[0,1,1]
	s_nop 0
	v_pk_fma_f32 v[110:111], v[132:133], v[168:169], v[110:111] op_sel_hi:[0,1,1]
	v_pk_fma_f32 v[112:113], v[132:133], v[166:167], v[112:113] op_sel_hi:[0,1,1]
	s_nop 0
	v_pk_fma_f32 v[112:113], v[134:135], v[170:171], v[112:113] op_sel_hi:[0,1,1]
	v_pk_fma_f32 v[110:111], v[134:135], v[172:173], v[110:111] op_sel_hi:[0,1,1]
	s_nop 0
	v_pk_fma_f32 v[110:111], v[108:109], v[176:177], v[110:111] op_sel_hi:[0,1,1]
	v_pk_fma_f32 v[108:109], v[108:109], v[174:175], v[112:113] op_sel_hi:[0,1,1]
	s_nop 0
	v_pk_fma_f32 v[112:113], v[136:137], v[178:179], v[108:109] op_sel_hi:[0,1,1]
	v_pk_fma_f32 v[104:105], v[136:137], v[180:181], v[110:111] op_sel_hi:[0,1,1]
	s_nop 0
	v_pk_fma_f32 v[104:105], v[102:103], v[194:195], v[104:105] op_sel_hi:[0,1,1]
	v_pk_fma_f32 v[102:103], v[102:103], v[192:193], v[112:113] op_sel_hi:[0,1,1]
	v_max_f32_e64 v63, -v102, 0
	v_mul_f32_e64 v102, |v102|, s43
	v_exp_f32_e32 v102, v102
	s_nop 0
	v_add_f32_e32 v102, 1.0, v102
	v_cmp_gt_f32_e32 vcc, s50, v102
	s_nop 1
	v_cndmask_b32_e64 v106, 0, 32, vcc
	v_ldexp_f32 v102, v102, v106
	v_log_f32_e32 v102, v102
	s_nop 0
	v_mul_f32_e32 v106, 0x3f317217, v102
	v_fma_f32 v106, v102, s51, -v106
	v_fmac_f32_e32 v106, 0x3377d1cf, v102
	v_fmac_f32_e32 v106, 0x3f317217, v102
	v_cmp_lt_f32_e64 s[0:1], |v102|, s65
	s_nop 1
	v_cndmask_b32_e64 v102, v102, v106, s[0:1]
	v_cndmask_b32_e32 v106, 0, v199, vcc
	v_sub_f32_e32 v102, v102, v106
	v_add_f32_e32 v63, v63, v102
	v_max_f32_e64 v102, -v103, 0
	v_mul_f32_e64 v103, |v103|, s43
	v_exp_f32_e32 v103, v103
	v_mul_f32_e32 v63, 0xbd800000, v63
	v_mul_f32_e32 v63, 0x3fb8aa3b, v63
	v_exp_f32_e32 v63, v63
	v_add_f32_e32 v103, 1.0, v103
	v_cmp_gt_f32_e32 vcc, s50, v103
	v_sub_f32_e32 v63, 1.0, v63
	s_nop 0
	v_cndmask_b32_e64 v106, 0, 32, vcc
	v_ldexp_f32 v103, v103, v106
	v_log_f32_e32 v103, v103
	s_nop 0
	v_mul_f32_e32 v106, 0x3f317217, v103
	v_fma_f32 v106, v103, s51, -v106
	v_fmac_f32_e32 v106, 0x3377d1cf, v103
	v_fmac_f32_e32 v106, 0x3f317217, v103
	v_cmp_lt_f32_e64 s[0:1], |v103|, s65
	s_nop 1
	v_cndmask_b32_e64 v103, v103, v106, s[0:1]
	v_cndmask_b32_e32 v106, 0, v199, vcc
	v_sub_f32_e32 v103, v103, v106
	v_add_f32_e32 v102, v102, v103
	v_max_f32_e64 v103, -v104, 0
	v_mul_f32_e64 v104, |v104|, s43
	v_exp_f32_e32 v104, v104
	v_mul_f32_e32 v102, 0xbd800000, v102
	v_mul_f32_e32 v102, 0x3fb8aa3b, v102
	v_exp_f32_e32 v102, v102
	v_add_f32_e32 v104, 1.0, v104
	v_cmp_gt_f32_e32 vcc, s50, v104
	v_sub_f32_e32 v102, 1.0, v102
	s_nop 0
	v_cndmask_b32_e64 v106, 0, 32, vcc
	v_ldexp_f32 v104, v104, v106
	v_log_f32_e32 v104, v104
	v_cvt_pk_bf16_f32 v102, v63, v102
	s_nop 0
	v_mul_f32_e32 v106, 0x3f317217, v104
	v_fma_f32 v106, v104, s51, -v106
	v_fmac_f32_e32 v106, 0x3377d1cf, v104
	v_fmac_f32_e32 v106, 0x3f317217, v104
	v_cmp_lt_f32_e64 s[0:1], |v104|, s65
	s_nop 1
	v_cndmask_b32_e64 v104, v104, v106, s[0:1]
	v_cndmask_b32_e32 v106, 0, v199, vcc
	v_sub_f32_e32 v104, v104, v106
	v_add_f32_e32 v103, v103, v104
	v_max_f32_e64 v104, -v105, 0
	v_mul_f32_e64 v105, |v105|, s43
	v_exp_f32_e32 v105, v105
	v_mul_f32_e32 v103, 0xbd800000, v103
	v_mul_f32_e32 v103, 0x3fb8aa3b, v103
	v_exp_f32_e32 v103, v103
	v_add_f32_e32 v105, 1.0, v105
	v_cmp_gt_f32_e32 vcc, s50, v105
	v_sub_f32_e32 v103, 1.0, v103
	s_nop 0
	v_cndmask_b32_e64 v106, 0, 32, vcc
	v_ldexp_f32 v105, v105, v106
	v_log_f32_e32 v105, v105
	s_nop 0
	v_mul_f32_e32 v106, 0x3f317217, v105
	v_fma_f32 v106, v105, s51, -v106
	v_fmac_f32_e32 v106, 0x3377d1cf, v105
	v_fmac_f32_e32 v106, 0x3f317217, v105
	v_cmp_lt_f32_e64 s[0:1], |v105|, s65
	s_nop 1
	v_cndmask_b32_e64 v105, v105, v106, s[0:1]
	v_cndmask_b32_e32 v106, 0, v199, vcc
	v_sub_f32_e32 v105, v105, v106
	v_add_f32_e32 v104, v104, v105
	v_mul_f32_e32 v104, 0xbd800000, v104
	v_mul_f32_e32 v104, 0x3fb8aa3b, v104
	v_exp_f32_e32 v104, v104
	v_readlane_b32 s0, v253, 26
	v_readlane_b32 s1, v253, 27
	v_cmp_lt_i32_e32 vcc, s53, v62
	v_sub_f32_e32 v104, 1.0, v104
	v_cvt_pk_bf16_f32 v103, v103, v104
	v_lshl_add_u64 v[104:105], s[22:23], 0, v[100:101]
	v_lshl_add_u64 v[92:93], v[92:93], 0, s[0:1]
	v_lshl_add_u64 v[98:99], v[98:99], 0, s[0:1]
	v_lshl_add_u64 v[100:101], v[100:101], 0, s[0:1]
	s_or_b64 s[30:31], vcc, s[30:31]
	global_store_dwordx2 v[104:105], v[102:103], off
	s_andn2_b64 exec, exec, s[30:31]
	s_cbranch_execz .LBB0_274
